# final RMSNorm loop: gain hoisted, next iteration prefetched ahead of the store; mixnorm loop: gains hoisted, next row prefetched; attention gathers: index reads batched; conv loop: store not waited
# speedup vs baseline: 1.2150x; 1.0180x over previous
.LBB0_442:
	s_mul_hi_i32 s16, s28, 0x2aaaaaab
	s_lshr_b32 s17, s16, 31
	s_ashr_i32 s29, s16, 2
	s_add_i32 s29, s29, s17
	s_mul_i32 s16, s29, 24
	s_sub_i32 s16, s28, s16
	s_mov_b64 s[14:15], s[0:1]
	s_lshl_b32 s30, s16, 6
	s_mov_b64 s[16:17], s[0:1]
	s_load_dwordx2 s[16:17], s[16:17], 0x50
	v_or_b32_e32 v0, s30, v45
	v_ashrrev_i32_e32 v1, 31, v0
	v_lshlrev_b64 v[0:1], 2, v[0:1]
	s_mov_b64 s[34:35], s[0:1]
	s_waitcnt lgkmcnt(0)
	v_lshl_add_u64 v[12:13], s[16:17], 0, v[0:1]
	v_add_co_u32_e32 v18, vcc, s3, v12
	s_load_dwordx2 s[34:35], s[34:35], 0x58
	s_nop 0
	v_addc_co_u32_e32 v19, vcc, 0, v13, vcc
	v_add_co_u32_e32 v32, vcc, 0x3000, v12
	v_lshl_add_u64 v[14:15], v[12:13], 0, s[8:9]
	s_nop 0
	v_addc_co_u32_e32 v33, vcc, 0, v13, vcc
	v_add_co_u32_e32 v48, vcc, 0x4000, v12
	v_lshl_add_u64 v[16:17], v[12:13], 0, s[10:11]
	s_nop 0
	v_addc_co_u32_e32 v49, vcc, 0, v13, vcc
	v_lshl_add_u64 v[40:41], v[12:13], 0, s[12:13]
	s_waitcnt lgkmcnt(0)
	v_lshl_add_u64 v[42:43], s[34:35], 0, v[0:1]
	global_load_dwordx4 v[0:3], v[12:13], off offset:16
	global_load_dwordx4 v[20:23], v[12:13], off
	global_load_dwordx4 v[28:31], v[18:19], off offset:2048
	global_load_dwordx4 v[24:27], v[32:33], off
	global_load_dwordx4 v[8:11], v[14:15], off offset:16
	global_load_dwordx4 v[4:7], v[16:17], off offset:16
	s_nop 0
	global_load_dwordx4 v[32:35], v[48:49], off offset:2048
	global_load_dwordx4 v[12:15], v[40:41], off offset:16
	global_load_dwordx4 v[16:19], v[42:43], off offset:16
	global_load_dwordx4 v[36:39], v[42:43], off
	s_and_saveexec_b64 s[16:17], s[6:7]
	ds_write_b128 v56, v[62:65] offset:43600
	s_or_b64 exec, exec, s[16:17]
	s_load_dwordx2 s[16:17], s[14:15], 0x100
	s_lshl_b32 s14, s29, 12
	v_add_u32_e32 v46, s30, v51
	v_or_b32_e32 v42, s14, v50
	v_lshlrev_b64 v[48:49], 1, v[46:47]
	s_waitcnt lgkmcnt(0)
	v_mov_b64_e32 v[40:41], s[16:17]
	v_mad_i64_i32 v[40:41], s[30:31], v42, s27, v[40:41]
	v_lshl_add_u64 v[40:41], v[40:41], 0, v[48:49]
	global_load_dwordx4 v[40:43], v[40:41], off
	v_lshl_add_u64 v[48:49], s[16:17], 0, v[48:49]
	s_mov_b32 s15, 0
	s_mov_b32 s16, 0
	s_waitcnt vmcnt(0)
.LBB0_445:
	v_lshl_add_u32 v46, s16, 6, v50
	v_cmp_gt_i32_e32 vcc, 3, v46
	s_add_i32 s17, s14, s15
	v_mad_u64_u32 v[66:67], s[30:31], v46, s26, v[44:45]
	v_cndmask_b32_e32 v61, -3, v53, vcc
	v_cmp_gt_i32_e32 vcc, 2, v46
	s_waitcnt vmcnt(1)
	ds_write_b128 v66, v[40:43] offset:16384
	v_add_u32_e32 v40, s17, v52
	v_cndmask_b32_e32 v67, -2, v54, vcc
	v_add_u32_e32 v42, v61, v46
	v_add_u32_e32 v43, v67, v46
	v_mad_i64_i32 v[40:41], s[30:31], v40, s27, v[48:49]
	v_mad_u64_u32 v[66:67], s[30:31], v42, s26, v[44:45]
	v_mad_u64_u32 v[70:71], s[30:31], v43, s26, v[44:45]
	global_load_dwordx4 v[40:43], v[40:41], off
	v_cmp_gt_i32_e32 vcc, 1, v46
	v_add_u32_e32 v69, 0xc0, v46
	s_waitcnt lgkmcnt(0)
	v_cndmask_b32_e32 v68, -1, v55, vcc
	v_cmp_gt_i32_e32 vcc, 0, v46
	v_add_u32_e32 v61, v68, v46
	v_add_u32_e32 v68, s17, v50
	v_cndmask_b32_e32 v46, v46, v69, vcc
	v_mad_u64_u32 v[74:75], s[30:31], v61, s26, v[44:45]
	v_mad_u64_u32 v[78:79], s[30:31], v46, s26, v[44:45]
	v_mad_i64_i32 v[82:83], s[30:31], v68, s27, v[48:49]
	s_barrier
	ds_read_b128 v[66:69], v66 offset:16384
	ds_read_b128 v[70:73], v70 offset:16384
	ds_read_b128 v[74:77], v74 offset:16384
	ds_read_b128 v[78:81], v78 offset:16384
	s_add_i32 s29, s16, 1
	s_waitcnt lgkmcnt(3)
	v_lshlrev_b32_e32 v84, 16, v66
	v_and_b32_e32 v85, 0xffff0000, v66
	v_lshlrev_b32_e32 v66, 16, v67
	v_and_b32_e32 v67, 0xffff0000, v67
	v_lshlrev_b32_e32 v92, 16, v68
	v_and_b32_e32 v93, 0xffff0000, v68
	v_lshlrev_b32_e32 v68, 16, v69
	v_and_b32_e32 v69, 0xffff0000, v69
	s_waitcnt lgkmcnt(2)
	v_lshlrev_b32_e32 v86, 16, v70
	v_and_b32_e32 v87, 0xffff0000, v70
	v_lshlrev_b32_e32 v70, 16, v71
	v_and_b32_e32 v71, 0xffff0000, v71
	v_lshlrev_b32_e32 v94, 16, v72
	v_and_b32_e32 v95, 0xffff0000, v72
	v_lshlrev_b32_e32 v72, 16, v73
	v_and_b32_e32 v73, 0xffff0000, v73
	v_pk_fma_f32 v[84:85], v[20:21], v[84:85], v[36:37]
	v_pk_fma_f32 v[66:67], v[22:23], v[66:67], v[38:39]
	v_pk_fma_f32 v[92:93], v[0:1], v[92:93], v[16:17]
	v_pk_fma_f32 v[68:69], v[2:3], v[68:69], v[18:19]
	s_waitcnt lgkmcnt(1)
	v_lshlrev_b32_e32 v88, 16, v74
	v_and_b32_e32 v89, 0xffff0000, v74
	v_lshlrev_b32_e32 v74, 16, v75
	v_and_b32_e32 v75, 0xffff0000, v75
	v_lshlrev_b32_e32 v96, 16, v76
	v_and_b32_e32 v97, 0xffff0000, v76
	v_lshlrev_b32_e32 v76, 16, v77
	v_and_b32_e32 v77, 0xffff0000, v77
	v_pk_fma_f32 v[84:85], v[28:29], v[86:87], v[84:85]
	v_pk_fma_f32 v[66:67], v[30:31], v[70:71], v[66:67]
	v_pk_fma_f32 v[70:71], v[8:9], v[94:95], v[92:93]
	v_pk_fma_f32 v[68:69], v[10:11], v[72:73], v[68:69]
	s_waitcnt lgkmcnt(0)
	v_lshlrev_b32_e32 v90, 16, v78
	v_and_b32_e32 v91, 0xffff0000, v78
	v_lshlrev_b32_e32 v78, 16, v79
	v_and_b32_e32 v79, 0xffff0000, v79
	v_lshlrev_b32_e32 v98, 16, v80
	v_and_b32_e32 v99, 0xffff0000, v80
	v_lshlrev_b32_e32 v80, 16, v81
	v_and_b32_e32 v81, 0xffff0000, v81
	v_pk_fma_f32 v[72:73], v[24:25], v[88:89], v[84:85]
	v_pk_fma_f32 v[66:67], v[26:27], v[74:75], v[66:67]
	v_pk_fma_f32 v[70:71], v[4:5], v[96:97], v[70:71]
	v_pk_fma_f32 v[68:69], v[6:7], v[76:77], v[68:69]
	v_pk_fma_f32 v[72:73], v[32:33], v[90:91], v[72:73]
	v_pk_fma_f32 v[66:67], v[34:35], v[78:79], v[66:67]
	v_pk_fma_f32 v[70:71], v[12:13], v[98:99], v[70:71]
	v_pk_fma_f32 v[68:69], v[14:15], v[80:81], v[68:69]
	v_mul_f32_e32 v46, 0xbfb8aa3b, v72
	v_mul_f32_e32 v61, 0xbfb8aa3b, v73
	v_mul_f32_e32 v74, 0xbfb8aa3b, v66
	v_mul_f32_e32 v75, 0xbfb8aa3b, v67
	v_mul_f32_e32 v76, 0xbfb8aa3b, v70
	v_mul_f32_e32 v77, 0xbfb8aa3b, v71
	v_mul_f32_e32 v78, 0xbfb8aa3b, v68
	v_mul_f32_e32 v79, 0xbfb8aa3b, v69
	v_exp_f32_e32 v46, v46
	v_exp_f32_e32 v61, v61
	v_exp_f32_e32 v74, v74
	v_exp_f32_e32 v75, v75
	v_exp_f32_e32 v76, v76
	v_exp_f32_e32 v77, v77
	v_exp_f32_e32 v78, v78
	v_exp_f32_e32 v79, v79
	v_add_f32_e32 v46, 1.0, v46
	v_add_f32_e32 v61, 1.0, v61
	v_add_f32_e32 v80, 1.0, v74
	v_add_f32_e32 v81, 1.0, v75
	v_add_f32_e32 v84, 1.0, v76
	v_add_f32_e32 v85, 1.0, v77
	v_add_f32_e32 v86, 1.0, v78
	v_add_f32_e32 v87, 1.0, v79
	v_rcp_f32_e32 v74, v46
	v_rcp_f32_e32 v75, v61
	v_rcp_f32_e32 v76, v80
	v_rcp_f32_e32 v77, v81
	v_rcp_f32_e32 v78, v84
	v_rcp_f32_e32 v79, v85
	v_rcp_f32_e32 v80, v86
	v_rcp_f32_e32 v81, v87
	s_cmp_lg_u32 s16, 2
	s_cselect_b32 s16, s29, 0
	s_add_i32 s15, s15, 64
	v_pk_mul_f32 v[72:73], v[72:73], v[74:75]
	v_pk_mul_f32 v[74:75], v[66:67], v[76:77]
	v_pk_mul_f32 v[70:71], v[70:71], v[78:79]
	v_pk_mul_f32 v[76:77], v[68:69], v[80:81]
	s_cmpk_lg_i32 s15, 0xfc0
	v_cvt_pk_bf16_f32 v66, v72, v73
	v_cvt_pk_bf16_f32 v67, v74, v75
	v_cvt_pk_bf16_f32 v68, v70, v71
	v_cvt_pk_bf16_f32 v69, v76, v77
	global_store_dwordx4 v[82:83], v[66:69], off
	s_cbranch_scc1 .LBB0_445
	s_or_b32 s14, s14, 0xfc0
	s_waitcnt vmcnt(1)
	ds_write_b128 v57, v[40:43] offset:16384
	s_waitcnt lgkmcnt(0)
	s_barrier
	ds_read_b128 v[40:43], v58 offset:16384
	ds_read_b128 v[66:69], v59 offset:16384
	ds_read_b128 v[70:73], v60 offset:16384
	ds_read_b128 v[74:77], v57 offset:16384
	s_add_i32 s28, s28, s22
	s_waitcnt lgkmcnt(3)
	v_lshlrev_b32_e32 v78, 16, v40
	v_and_b32_e32 v79, 0xffff0000, v40
	v_pk_fma_f32 v[20:21], v[20:21], v[78:79], v[36:37]
	s_waitcnt lgkmcnt(2)
	v_lshlrev_b32_e32 v36, 16, v66
	v_and_b32_e32 v37, 0xffff0000, v66
	v_pk_fma_f32 v[20:21], v[28:29], v[36:37], v[20:21]
	s_waitcnt lgkmcnt(1)
	v_lshlrev_b32_e32 v28, 16, v70
	v_and_b32_e32 v29, 0xffff0000, v70
	v_pk_fma_f32 v[20:21], v[24:25], v[28:29], v[20:21]
	v_lshlrev_b32_e32 v28, 16, v41
	v_and_b32_e32 v29, 0xffff0000, v41
	v_pk_fma_f32 v[22:23], v[22:23], v[28:29], v[38:39]
	v_lshlrev_b32_e32 v28, 16, v67
	v_and_b32_e32 v29, 0xffff0000, v67
	v_pk_fma_f32 v[22:23], v[30:31], v[28:29], v[22:23]
	v_lshlrev_b32_e32 v28, 16, v71
	v_and_b32_e32 v29, 0xffff0000, v71
	v_pk_fma_f32 v[22:23], v[26:27], v[28:29], v[22:23]
	v_lshlrev_b32_e32 v28, 16, v42
	v_and_b32_e32 v29, 0xffff0000, v42
	v_pk_fma_f32 v[0:1], v[0:1], v[28:29], v[16:17]
	v_lshlrev_b32_e32 v16, 16, v68
	v_and_b32_e32 v17, 0xffff0000, v68
	v_pk_fma_f32 v[0:1], v[8:9], v[16:17], v[0:1]
	v_lshlrev_b32_e32 v8, 16, v72
	v_and_b32_e32 v9, 0xffff0000, v72
	v_pk_fma_f32 v[0:1], v[4:5], v[8:9], v[0:1]
	v_lshlrev_b32_e32 v8, 16, v43
	v_and_b32_e32 v9, 0xffff0000, v43
	v_pk_fma_f32 v[2:3], v[2:3], v[8:9], v[18:19]
	v_lshlrev_b32_e32 v8, 16, v69
	v_and_b32_e32 v9, 0xffff0000, v69
	s_waitcnt lgkmcnt(0)
	v_lshlrev_b32_e32 v4, 16, v76
	v_and_b32_e32 v5, 0xffff0000, v76
	v_pk_fma_f32 v[2:3], v[10:11], v[8:9], v[2:3]
	v_lshlrev_b32_e32 v8, 16, v73
	v_and_b32_e32 v9, 0xffff0000, v73
	v_lshlrev_b32_e32 v24, 16, v74
	v_and_b32_e32 v25, 0xffff0000, v74
	v_lshlrev_b32_e32 v26, 16, v75
	v_and_b32_e32 v27, 0xffff0000, v75
	v_pk_fma_f32 v[0:1], v[12:13], v[4:5], v[0:1]
	v_pk_fma_f32 v[2:3], v[6:7], v[8:9], v[2:3]
	v_lshlrev_b32_e32 v6, 16, v77
	v_and_b32_e32 v7, 0xffff0000, v77
	v_pk_fma_f32 v[20:21], v[32:33], v[24:25], v[20:21]
	v_pk_fma_f32 v[22:23], v[34:35], v[26:27], v[22:23]
	v_mul_f32_e32 v4, 0xbfb8aa3b, v0
	v_mul_f32_e32 v5, 0xbfb8aa3b, v1
	v_pk_fma_f32 v[2:3], v[14:15], v[6:7], v[2:3]
	v_mul_f32_e32 v24, 0xbfb8aa3b, v20
	v_mul_f32_e32 v25, 0xbfb8aa3b, v21
	v_mul_f32_e32 v26, 0xbfb8aa3b, v22
	v_mul_f32_e32 v27, 0xbfb8aa3b, v23
	v_exp_f32_e32 v4, v4
	v_exp_f32_e32 v5, v5
	v_mul_f32_e32 v6, 0xbfb8aa3b, v2
	v_mul_f32_e32 v7, 0xbfb8aa3b, v3
	v_exp_f32_e32 v24, v24
	v_exp_f32_e32 v25, v25
	v_exp_f32_e32 v26, v26
	v_exp_f32_e32 v27, v27
	v_exp_f32_e32 v6, v6
	v_exp_f32_e32 v7, v7
	v_add_f32_e32 v4, 1.0, v4
	v_add_f32_e32 v5, 1.0, v5
	v_add_f32_e32 v24, 1.0, v24
	v_add_f32_e32 v25, 1.0, v25
	v_add_f32_e32 v26, 1.0, v26
	v_add_f32_e32 v27, 1.0, v27
	v_rcp_f32_e32 v4, v4
	v_rcp_f32_e32 v5, v5
	v_add_f32_e32 v6, 1.0, v6
	v_add_f32_e32 v7, 1.0, v7
	v_rcp_f32_e32 v24, v24
	v_rcp_f32_e32 v25, v25
	v_rcp_f32_e32 v26, v26
	v_rcp_f32_e32 v27, v27
	v_rcp_f32_e32 v6, v6
	v_rcp_f32_e32 v7, v7
	v_pk_mul_f32 v[4:5], v[0:1], v[4:5]
	v_pk_mul_f32 v[8:9], v[20:21], v[24:25]
	v_pk_mul_f32 v[10:11], v[22:23], v[26:27]
	v_pk_mul_f32 v[6:7], v[2:3], v[6:7]
	v_cvt_pk_bf16_f32 v2, v4, v5
	v_add_u32_e32 v4, s14, v50
	v_cvt_pk_bf16_f32 v0, v8, v9
	v_cvt_pk_bf16_f32 v1, v10, v11
	v_cvt_pk_bf16_f32 v3, v6, v7
	v_mad_i64_i32 v[4:5], s[14:15], v4, s27, v[48:49]
	s_cmpk_gt_i32 s28, 0xbf
	global_store_dwordx4 v[4:5], v[0:3], off
	s_barrier
	s_cbranch_scc0 .LBB0_442

.LBB0_742:
	s_cmp_lt_i32 s62, 7
	s_cselect_b64 s[6:7], -1, 0
	s_cmp_gt_i32 s61, 6
	s_cselect_b64 s[8:9], -1, 0
	s_and_b64 s[6:7], s[6:7], s[8:9]
	s_andn2_b64 vcc, exec, s[6:7]
	s_cbranch_vccnz .LBB0_800
	v_lshrrev_b32_e32 v0, 6, v192
	v_lshl_add_u32 v30, s2, 3, v0
	s_mov_b32 s3, 0x8000
	s_mov_b64 s[8:9], s[0:1]
	s_mov_b64 s[10:11], s[0:1]
	s_mov_b64 s[12:13], s[0:1]
	v_cmp_gt_i32_e32 vcc, s3, v30
	s_and_saveexec_b64 s[6:7], vcc
	s_cbranch_execz .LBB0_746
	s_load_dwordx2 s[14:15], s[8:9], 0x100
	s_load_dwordx2 s[16:17], s[10:11], 0x48
	s_load_dwordx2 s[24:25], s[12:13], 0x78
	v_and_b32_e32 v1, 63, v192
	v_lshlrev_b32_e32 v0, 2, v1
	v_lshlrev_b32_e32 v2, 3, v1
	v_mov_b32_e32 v5, 0
	v_lshlrev_b32_e32 v4, 4, v1
	s_waitcnt lgkmcnt(0)
	v_lshl_add_u64 v[6:7], s[16:17], 0, v[4:5]
	v_or_b32_e32 v12, 0x100, v0
	v_or_b32_e32 v16, 0x200, v0
	v_or_b32_e32 v18, 0x300, v0
	v_lshlrev_b32_e32 v4, 5, v1
	v_or_b32_e32 v22, 0x200, v2
	v_mov_b64_e32 v[10:11], s[14:15]
	s_mov_b32 s14, 0x358637bd
	s_lshl_b32 s3, s22, 3
	v_lshl_add_u64 v[8:9], s[24:25], 0, v[4:5]
	s_mov_b64 s[8:9], 0
	s_movk_i32 s13, 0x2c00
	s_mov_b64 s[10:11], 0x1000
	v_lshlrev_b32_e32 v4, 1, v0
	v_lshlrev_b32_e32 v12, 1, v12
	v_mov_b32_e32 v13, v5
	s_mov_b32 s12, 0x3b800000
	v_mov_b64_e32 v[14:15], s[14:15]
	s_mov_b32 s17, 0x800000
	v_lshlrev_b32_e32 v16, 1, v16
	v_mov_b32_e32 v17, v5
	v_lshlrev_b32_e32 v18, 1, v18
	v_mov_b32_e32 v19, v5
	s_mov_b64 s[14:15], 0x1800
	v_lshlrev_b32_e32 v20, 1, v2
	v_mov_b32_e32 v21, v5
	v_lshlrev_b32_e32 v22, 1, v22
	v_mov_b32_e32 v23, v5
	s_mov_b32 s16, 0x3b000000
	s_movk_i32 s24, 0x7fff
	v_mad_i64_i32 v[172:173], s[26:27], v30, s13, v[10:11]
	v_lshl_add_u64 v[174:175], v[172:173], 0, v[4:5]
	global_load_dwordx2 v[140:141], v[174:175], off offset:2048
	global_load_dwordx2 v[142:143], v[174:175], off offset:2560
	global_load_dwordx2 v[144:145], v[174:175], off offset:3072
	global_load_dwordx2 v[146:147], v[174:175], off offset:3584
	v_lshl_add_u64 v[176:177], v[172:173], 0, s[10:11]
	v_lshl_add_u64 v[174:175], v[176:177], 0, v[4:5]
	global_load_dwordx2 v[148:149], v[174:175], off
	v_lshl_add_u64 v[174:175], v[176:177], 0, v[12:13]
	global_load_dwordx2 v[150:151], v[174:175], off
	v_lshl_add_u64 v[174:175], v[176:177], 0, v[16:17]
	global_load_dwordx2 v[152:153], v[174:175], off
	v_lshl_add_u64 v[174:175], v[176:177], 0, v[18:19]
	global_load_dwordx2 v[154:155], v[174:175], off
	v_lshl_add_u64 v[176:177], v[172:173], 0, s[14:15]
	v_lshl_add_u64 v[174:175], v[176:177], 0, v[20:21]
	global_load_dwordx4 v[156:159], v[174:175], off
	v_lshl_add_u64 v[174:175], v[176:177], 0, v[22:23]
	global_load_dwordx4 v[160:163], v[174:175], off
	global_load_dwordx4 v[100:103], v[6:7], off
	global_load_dwordx4 v[104:107], v[6:7], off offset:1024
	global_load_dwordx4 v[108:111], v[6:7], off offset:2048
	global_load_dwordx4 v[112:115], v[6:7], off offset:3072
	global_load_dwordx4 v[116:119], v[8:9], off
	global_load_dwordx4 v[120:123], v[8:9], off offset:16
	global_load_dwordx4 v[124:127], v[8:9], off offset:2048
	global_load_dwordx4 v[128:131], v[8:9], off offset:2064
	s_waitcnt vmcnt(0)
.LBB0_745:
	v_mad_i64_i32 v[26:27], s[26:27], v30, s13, v[10:11]
	v_lshl_add_u64 v[24:25], v[26:27], 0, s[10:11]
	v_lshl_add_u64 v[32:33], v[26:27], 0, s[14:15]
	v_lshl_add_u64 v[40:41], v[24:25], 0, v[4:5]
	v_lshl_add_u64 v[42:43], v[24:25], 0, v[12:13]
	v_lshl_add_u64 v[44:45], v[24:25], 0, v[16:17]
	v_lshl_add_u64 v[28:29], v[24:25], 0, v[18:19]
	v_lshl_add_u64 v[26:27], v[32:33], 0, v[20:21]
	v_lshl_add_u64 v[24:25], v[32:33], 0, v[22:23]
	v_add_u32_e32 v30, s3, v30
	v_min_i32_e32 v178, s24, v30
	s_waitcnt vmcnt(6)
	v_mov_b64_e32 v[34:35], v[140:141]
	v_mov_b64_e32 v[36:37], v[142:143]
	v_mov_b64_e32 v[38:39], v[144:145]
	v_mov_b64_e32 v[46:47], v[146:147]
	v_mov_b64_e32 v[32:33], v[148:149]
	v_mov_b64_e32 v[48:49], v[150:151]
	v_mov_b64_e32 v[50:51], v[152:153]
	v_mov_b64_e32 v[52:53], v[154:155]
	v_mov_b64_e32 v[164:165], v[156:157]
	v_mov_b64_e32 v[166:167], v[158:159]
	v_mov_b64_e32 v[168:169], v[160:161]
	v_mov_b64_e32 v[170:171], v[162:163]
	v_mov_b64_e32 v[0:1], v[100:101]
	v_mov_b64_e32 v[2:3], v[102:103]
	v_mad_i64_i32 v[172:173], s[26:27], v178, s13, v[10:11]
	v_lshl_add_u64 v[174:175], v[172:173], 0, v[4:5]
	global_load_dwordx2 v[140:141], v[174:175], off offset:2048
	global_load_dwordx2 v[142:143], v[174:175], off offset:2560
	global_load_dwordx2 v[144:145], v[174:175], off offset:3072
	global_load_dwordx2 v[146:147], v[174:175], off offset:3584
	v_lshl_add_u64 v[176:177], v[172:173], 0, s[10:11]
	v_lshl_add_u64 v[174:175], v[176:177], 0, v[4:5]
	global_load_dwordx2 v[148:149], v[174:175], off
	v_lshl_add_u64 v[174:175], v[176:177], 0, v[12:13]
	global_load_dwordx2 v[150:151], v[174:175], off
	v_lshl_add_u64 v[174:175], v[176:177], 0, v[16:17]
	global_load_dwordx2 v[152:153], v[174:175], off
	v_lshl_add_u64 v[174:175], v[176:177], 0, v[18:19]
	global_load_dwordx2 v[154:155], v[174:175], off
	v_lshl_add_u64 v[176:177], v[172:173], 0, s[14:15]
	v_lshl_add_u64 v[174:175], v[176:177], 0, v[20:21]
	global_load_dwordx4 v[156:159], v[174:175], off
	v_lshl_add_u64 v[174:175], v[176:177], 0, v[22:23]
	global_load_dwordx4 v[160:163], v[174:175], off
	v_lshlrev_b32_e32 v54, 16, v35
	v_and_b32_e32 v55, 0xffff0000, v35
	v_lshlrev_b32_e32 v56, 16, v34
	v_and_b32_e32 v57, 0xffff0000, v34
	v_lshlrev_b32_e32 v34, 16, v37
	v_and_b32_e32 v35, 0xffff0000, v37
	v_lshlrev_b32_e32 v58, 16, v36
	v_and_b32_e32 v59, 0xffff0000, v36
	v_lshlrev_b32_e32 v36, 16, v39
	v_and_b32_e32 v37, 0xffff0000, v39
	v_lshlrev_b32_e32 v60, 16, v38
	v_and_b32_e32 v61, 0xffff0000, v38
	v_lshlrev_b32_e32 v62, 16, v47
	v_and_b32_e32 v63, 0xffff0000, v47
	v_lshlrev_b32_e32 v64, 16, v46
	v_and_b32_e32 v65, 0xffff0000, v46
	v_lshlrev_b32_e32 v38, 16, v33
	v_and_b32_e32 v39, 0xffff0000, v33
	v_pk_mul_f32 v[46:47], v[54:55], v[54:55]
	v_lshlrev_b32_e32 v66, 16, v32
	v_and_b32_e32 v67, 0xffff0000, v32
	v_pk_mul_f32 v[32:33], v[56:57], v[56:57]
	v_lshlrev_b32_e32 v68, 16, v49
	v_and_b32_e32 v69, 0xffff0000, v49
	v_pk_mul_f32 v[70:71], v[34:35], v[34:35]
	v_lshlrev_b32_e32 v72, 16, v48
	v_and_b32_e32 v73, 0xffff0000, v48
	v_pk_mul_f32 v[48:49], v[58:59], v[58:59]
	v_pk_mul_f32 v[80:81], v[62:63], v[62:63]
	v_pk_mul_f32 v[82:83], v[64:65], v[64:65]
	v_mul_f32_e32 v31, 0xbfb8aa3b, v66
	v_mul_f32_e32 v84, 0xbfb8aa3b, v67
	v_add_f32_e32 v46, v46, v47
	v_add_f32_e32 v32, v32, v33
	v_add_f32_e32 v70, v70, v71
	v_add_f32_e32 v48, v48, v49
	v_mul_f32_e32 v33, 0xbfb8aa3b, v38
	v_mul_f32_e32 v47, 0xbfb8aa3b, v39
	v_add_f32_e32 v80, v80, v81
	v_add_f32_e32 v81, v82, v83
	v_exp_f32_e32 v31, v31
	v_exp_f32_e32 v82, v84
	v_add_f32_e32 v32, v32, v46
	v_add_f32_e32 v48, v48, v70
	v_mul_f32_e32 v85, 0xbfb8aa3b, v72
	v_exp_f32_e32 v33, v33
	v_exp_f32_e32 v46, v47
	v_add_f32_dpp v32, v32, v32 quad_perm:[1,0,3,2] row_mask:0xf bank_mask:0xf bound_ctrl:1
	v_add_f32_dpp v48, v48, v48 quad_perm:[1,0,3,2] row_mask:0xf bank_mask:0xf bound_ctrl:1
	v_lshlrev_b32_e32 v74, 16, v51
	v_and_b32_e32 v75, 0xffff0000, v51
	v_pk_mul_f32 v[76:77], v[36:37], v[36:37]
	v_lshlrev_b32_e32 v78, 16, v50
	v_and_b32_e32 v79, 0xffff0000, v50
	v_pk_mul_f32 v[50:51], v[60:61], v[60:61]
	v_mul_f32_e32 v86, 0xbfb8aa3b, v73
	v_exp_f32_e32 v47, v85
	v_add_f32_dpp v32, v32, v32 quad_perm:[2,3,0,1] row_mask:0xf bank_mask:0xf bound_ctrl:1
	v_add_f32_dpp v48, v48, v48 quad_perm:[2,3,0,1] row_mask:0xf bank_mask:0xf bound_ctrl:1
	v_mul_f32_e32 v49, 0xbfb8aa3b, v68
	v_mul_f32_e32 v71, 0xbfb8aa3b, v69
	v_mul_f32_e32 v87, 0xbfb8aa3b, v78
	v_add_f32_e32 v76, v76, v77
	v_add_f32_e32 v50, v50, v51
	v_mul_f32_e32 v77, 0xbfb8aa3b, v75
	v_exp_f32_e32 v83, v86
	v_add_f32_dpp v32, v32, v32 row_half_mirror row_mask:0xf bank_mask:0xf bound_ctrl:1
	v_add_f32_dpp v48, v48, v48 row_half_mirror row_mask:0xf bank_mask:0xf bound_ctrl:1
	v_exp_f32_e32 v49, v49
	v_exp_f32_e32 v70, v71
	v_exp_f32_e32 v71, v87
	v_add_f32_e32 v50, v50, v76
	v_exp_f32_e32 v76, v77
	v_add_f32_e32 v77, v81, v80
	v_add_f32_e32 v31, 1.0, v31
	v_add_f32_e32 v80, 1.0, v82
	v_add_f32_dpp v81, v32, v32 row_mirror row_mask:0xf bank_mask:0xf bound_ctrl:1
	v_add_f32_dpp v87, v48, v48 row_mirror row_mask:0xf bank_mask:0xf bound_ctrl:1
	v_add_f32_e32 v82, 1.0, v33
	v_add_f32_e32 v85, 1.0, v46
	v_rcp_f32_e32 v32, v31
	v_rcp_f32_e32 v33, v80
	v_mov_b32_e32 v31, v81
	v_mov_b32_e32 v80, v87
	v_add_f32_e32 v86, 1.0, v47
	v_rcp_f32_e32 v46, v82
	v_rcp_f32_e32 v47, v85
	v_permlane16_swap_b32_e32 v81, v31
	v_permlane16_swap_b32_e32 v87, v80
	v_mul_f32_e32 v88, 0xbfb8aa3b, v79
	v_add_f32_e32 v83, 1.0, v83
	v_add_f32_e32 v81, v81, v31
	v_add_f32_e32 v80, v87, v80
	v_exp_f32_e32 v84, v88
	v_add_f32_e32 v88, 1.0, v49
	v_rcp_f32_e32 v49, v83
	v_mov_b32_e32 v83, v81
	v_mov_b32_e32 v82, v80
	s_nop 0
	v_permlane32_swap_b32_e32 v81, v83
	v_permlane32_swap_b32_e32 v80, v82
	v_pk_mul_f32 v[38:39], v[46:47], v[38:39]
	v_pk_add_f32 v[46:47], v[80:81], v[82:83]
	v_pk_mul_f32 v[32:33], v[32:33], v[66:67]
	v_pk_fma_f32 v[46:47], v[46:47], s[12:13], v[14:15] op_sel_hi:[1,0,0]
	v_mul_f32_e32 v51, 0xbfb8aa3b, v74
	v_mul_f32_e32 v31, 0x4b800000, v47
	v_cmp_gt_f32_e32 vcc, s17, v47
	v_exp_f32_e32 v51, v51
	v_add_f32_dpp v50, v50, v50 quad_perm:[1,0,3,2] row_mask:0xf bank_mask:0xf bound_ctrl:1
	v_cndmask_b32_e32 v31, v47, v31, vcc
	v_rsq_f32_e32 v31, v31
	v_add_f32_dpp v50, v50, v50 quad_perm:[2,3,0,1] row_mask:0xf bank_mask:0xf bound_ctrl:1
	v_add_f32_e32 v70, 1.0, v70
	v_rcp_f32_e32 v48, v86
	v_mul_f32_e32 v47, 0x45800000, v31
	v_cndmask_b32_e32 v66, v31, v47, vcc
	v_pk_mul_f32 v[56:57], v[66:67], v[56:57] op_sel_hi:[0,1]
	v_pk_mul_f32 v[54:55], v[66:67], v[54:55] op_sel_hi:[0,1]
	v_pk_mul_f32 v[0:1], v[0:1], v[56:57]
	v_pk_mul_f32 v[2:3], v[2:3], v[54:55]
	v_pk_mul_f32 v[0:1], v[32:33], v[0:1]
	v_pk_mul_f32 v[2:3], v[38:39], v[2:3]
	v_cvt_pk_bf16_f32 v0, v0, v1
	v_cvt_pk_bf16_f32 v1, v2, v3
	global_store_dwordx2 v[40:41], v[0:1], off
	v_mul_f32_e32 v31, 0x4b800000, v46
	v_cmp_gt_f32_e32 vcc, s17, v46
	v_add_f32_dpp v50, v50, v50 row_half_mirror row_mask:0xf bank_mask:0xf bound_ctrl:1
	v_add_f32_e32 v90, 1.0, v51
	v_cndmask_b32_e32 v31, v46, v31, vcc
	v_rsq_f32_e32 v31, v31
	v_add_f32_dpp v89, v50, v50 row_mirror row_mask:0xf bank_mask:0xf bound_ctrl:1
	v_rcp_f32_e32 v50, v88
	v_rcp_f32_e32 v51, v70
	v_mul_f32_e32 v46, 0x45800000, v31
	v_cndmask_b32_e32 v46, v31, v46, vcc
	v_pk_mul_f32 v[38:39], v[48:49], v[72:73]
	v_pk_mul_f32 v[48:49], v[46:47], v[58:59] op_sel_hi:[0,1]
	v_pk_mul_f32 v[34:35], v[46:47], v[34:35] op_sel_hi:[0,1]
	v_pk_mul_f32 v[40:41], v[50:51], v[68:69]
	v_add_f32_dpp v77, v77, v77 quad_perm:[1,0,3,2] row_mask:0xf bank_mask:0xf bound_ctrl:1
	v_add_f32_e32 v71, 1.0, v71
	v_add_f32_e32 v84, 1.0, v84
	v_add_f32_dpp v77, v77, v77 quad_perm:[2,3,0,1] row_mask:0xf bank_mask:0xf bound_ctrl:1
	v_rcp_f32_e32 v70, v71
	v_rcp_f32_e32 v71, v84
	v_add_f32_dpp v77, v77, v77 row_half_mirror row_mask:0xf bank_mask:0xf bound_ctrl:1
	v_mov_b32_e32 v84, v89
	s_nop 1
	v_permlane16_swap_b32_e32 v89, v84
	v_add_f32_dpp v92, v77, v77 row_mirror row_mask:0xf bank_mask:0xf bound_ctrl:1
	v_mov_b32_e32 v85, v92
	s_nop 1
	v_permlane16_swap_b32_e32 v92, v85
	v_add_f32_e32 v33, v89, v84
	v_add_f32_e32 v32, v92, v85
	v_add_f32_e32 v91, 1.0, v76
	v_rcp_f32_e32 v76, v90
	v_rcp_f32_e32 v77, v91
	v_pk_mul_f32 v[0:1], v[104:105], v[48:49]
	v_pk_mul_f32 v[2:3], v[106:107], v[34:35]
	v_pk_mul_f32 v[0:1], v[38:39], v[0:1]
	v_pk_mul_f32 v[2:3], v[40:41], v[2:3]
	v_cvt_pk_bf16_f32 v0, v0, v1
	v_cvt_pk_bf16_f32 v1, v2, v3
	global_store_dwordx2 v[42:43], v[0:1], off
	v_mov_b32_e32 v35, v33
	v_mov_b32_e32 v34, v32
	s_nop 0
	v_permlane32_swap_b32_e32 v33, v35
	v_permlane32_swap_b32_e32 v32, v34
	v_pk_add_f32 v[32:33], v[32:33], v[34:35]
	v_pk_mul_f32 v[38:39], v[70:71], v[78:79]
	v_pk_fma_f32 v[42:43], v[32:33], s[12:13], v[14:15] op_sel_hi:[1,0,0]
	v_pk_mul_f32 v[40:41], v[76:77], v[74:75]
	v_mul_f32_e32 v31, 0x4b800000, v43
	v_cmp_gt_f32_e32 vcc, s17, v43
	s_nop 1
	v_cndmask_b32_e32 v31, v43, v31, vcc
	v_rsq_f32_e32 v31, v31
	s_nop 0
	v_mul_f32_e32 v32, 0x45800000, v31
	v_cndmask_b32_e32 v32, v31, v32, vcc
	v_pk_mul_f32 v[34:35], v[32:33], v[60:61] op_sel_hi:[0,1]
	v_pk_mul_f32 v[32:33], v[32:33], v[36:37] op_sel_hi:[0,1]
	v_cmp_gt_f32_e32 vcc, s17, v42
	v_pk_mul_f32 v[0:1], v[108:109], v[34:35]
	v_pk_mul_f32 v[2:3], v[110:111], v[32:33]
	v_pk_mul_f32 v[0:1], v[38:39], v[0:1]
	v_pk_mul_f32 v[2:3], v[40:41], v[2:3]
	v_cvt_pk_bf16_f32 v0, v0, v1
	v_cvt_pk_bf16_f32 v1, v2, v3
	global_store_dwordx2 v[44:45], v[0:1], off
	v_mov_b64_e32 v[32:33], v[164:165]
	v_mov_b64_e32 v[34:35], v[166:167]
	v_mov_b64_e32 v[36:37], v[168:169]
	v_mov_b64_e32 v[38:39], v[170:171]
	v_lshlrev_b32_e32 v44, 16, v52
	v_and_b32_e32 v45, 0xffff0000, v52
	v_mul_f32_e32 v31, 0xbfb8aa3b, v44
	v_lshlrev_b32_e32 v40, 16, v53
	v_and_b32_e32 v41, 0xffff0000, v53
	v_exp_f32_e32 v31, v31
	v_lshlrev_b32_e32 v52, 16, v32
	v_and_b32_e32 v53, 0xffff0000, v32
	v_mul_f32_e32 v32, 0xbfb8aa3b, v45
	v_lshlrev_b32_e32 v48, 16, v34
	v_and_b32_e32 v49, 0xffff0000, v34
	v_lshlrev_b32_e32 v50, 16, v33
	v_and_b32_e32 v51, 0xffff0000, v33
	v_mul_f32_e32 v33, 0xbfb8aa3b, v40
	v_mul_f32_e32 v34, 0xbfb8aa3b, v41
	v_exp_f32_e32 v32, v32
	v_exp_f32_e32 v33, v33
	v_exp_f32_e32 v34, v34
	v_add_f32_e32 v31, 1.0, v31
	v_lshlrev_b32_e32 v46, 16, v35
	v_and_b32_e32 v47, 0xffff0000, v35
	v_add_f32_e32 v35, 1.0, v32
	v_rcp_f32_e32 v32, v31
	v_mul_f32_e32 v31, 0x4b800000, v42
	v_add_f32_e32 v43, 1.0, v33
	v_add_f32_e32 v54, 1.0, v34
	v_cndmask_b32_e32 v31, v42, v31, vcc
	v_rcp_f32_e32 v33, v35
	v_rcp_f32_e32 v34, v43
	v_rcp_f32_e32 v35, v54
	v_rsq_f32_e32 v31, v31
	v_pk_mul_f32 v[32:33], v[32:33], v[44:45]
	v_lshlrev_b32_e32 v44, 16, v36
	v_pk_mul_f32 v[34:35], v[34:35], v[40:41]
	v_mul_f32_e32 v40, 0x45800000, v31
	v_cndmask_b32_e32 v40, v31, v40, vcc
	v_pk_mul_f32 v[42:43], v[40:41], v[64:65] op_sel_hi:[0,1]
	v_pk_mul_f32 v[40:41], v[40:41], v[62:63] op_sel_hi:[0,1]
	v_pk_mul_f32 v[0:1], v[112:113], v[42:43]
	v_pk_mul_f32 v[2:3], v[114:115], v[40:41]
	v_pk_mul_f32 v[0:1], v[32:33], v[0:1]
	v_pk_mul_f32 v[2:3], v[34:35], v[2:3]
	v_cvt_pk_bf16_f32 v0, v0, v1
	v_cvt_pk_bf16_f32 v1, v2, v3
	global_store_dwordx2 v[28:29], v[0:1], off
	v_and_b32_e32 v45, 0xffff0000, v36
	v_lshlrev_b32_e32 v40, 16, v39
	v_and_b32_e32 v41, 0xffff0000, v39
	v_lshlrev_b32_e32 v42, 16, v38
	v_and_b32_e32 v43, 0xffff0000, v38
	v_lshlrev_b32_e32 v38, 16, v37
	v_and_b32_e32 v39, 0xffff0000, v37
	v_pk_mul_f32 v[56:57], v[52:53], v[52:53]
	v_pk_mul_f32 v[64:65], v[44:45], v[44:45]
	v_pk_mul_f32 v[54:55], v[50:51], v[50:51]
	v_pk_mul_f32 v[62:63], v[38:39], v[38:39]
	v_add_f32_e32 v31, v56, v57
	v_add_f32_e32 v56, v64, v65
	v_add_f32_e32 v31, v54, v31
	v_add_f32_e32 v54, v62, v56
	v_pk_mul_f32 v[36:37], v[48:49], v[48:49]
	v_pk_mul_f32 v[60:61], v[42:43], v[42:43]
	v_add_f32_e32 v31, v55, v31
	v_add_f32_e32 v54, v63, v54
	v_add_f32_e32 v31, v36, v31
	v_add_f32_e32 v36, v60, v54
	v_pk_mul_f32 v[28:29], v[46:47], v[46:47]
	v_pk_mul_f32 v[58:59], v[40:41], v[40:41]
	v_add_f32_e32 v31, v37, v31
	v_add_f32_e32 v36, v61, v36
	v_add_f32_e32 v28, v28, v31
	v_add_f32_e32 v31, v58, v36
	v_add_f32_e32 v28, v29, v28
	v_add_f32_e32 v29, v59, v31
	s_nop 0
	v_add_f32_dpp v28, v28, v28 quad_perm:[1,0,3,2] row_mask:0xf bank_mask:0xf bound_ctrl:1
	v_add_f32_dpp v29, v29, v29 quad_perm:[1,0,3,2] row_mask:0xf bank_mask:0xf bound_ctrl:1
	s_nop 0
	v_add_f32_dpp v28, v28, v28 quad_perm:[2,3,0,1] row_mask:0xf bank_mask:0xf bound_ctrl:1
	v_add_f32_dpp v29, v29, v29 quad_perm:[2,3,0,1] row_mask:0xf bank_mask:0xf bound_ctrl:1
	s_nop 0
	v_add_f32_dpp v28, v28, v28 row_half_mirror row_mask:0xf bank_mask:0xf bound_ctrl:1
	v_add_f32_dpp v29, v29, v29 row_half_mirror row_mask:0xf bank_mask:0xf bound_ctrl:1
	s_nop 0
	v_add_f32_dpp v28, v28, v28 row_mirror row_mask:0xf bank_mask:0xf bound_ctrl:1
	v_add_f32_dpp v31, v29, v29 row_mirror row_mask:0xf bank_mask:0xf bound_ctrl:1
	v_mov_b32_e32 v29, v28
	v_mov_b32_e32 v36, v31
	s_nop 0
	v_permlane16_swap_b32_e32 v28, v29
	v_permlane16_swap_b32_e32 v31, v36
	v_add_f32_e32 v29, v28, v29
	v_add_f32_e32 v28, v31, v36
	v_mov_b32_e32 v37, v29
	v_mov_b32_e32 v36, v28
	s_nop 0
	v_permlane32_swap_b32_e32 v29, v37
	v_permlane32_swap_b32_e32 v28, v36
	v_pk_add_f32 v[28:29], v[28:29], v[36:37]
	s_nop 0
	v_pk_fma_f32 v[36:37], v[28:29], s[16:17], v[14:15] op_sel_hi:[1,0,0]
	s_nop 0
	v_mul_f32_e32 v28, 0x4b800000, v37
	v_cmp_gt_f32_e32 vcc, s17, v37
	v_mul_f32_e32 v31, 0x4b800000, v36
	s_nop 0
	v_cndmask_b32_e32 v28, v37, v28, vcc
	v_rsq_f32_e32 v28, v28
	s_nop 0
	v_mul_f32_e32 v29, 0x45800000, v28
	v_cndmask_b32_e32 v28, v28, v29, vcc
	v_pk_mul_f32 v[52:53], v[28:29], v[52:53] op_sel_hi:[0,1]
	v_pk_mul_f32 v[50:51], v[28:29], v[50:51] op_sel_hi:[0,1]
	v_pk_mul_f32 v[48:49], v[28:29], v[48:49] op_sel_hi:[0,1]
	v_pk_mul_f32 v[28:29], v[28:29], v[46:47] op_sel_hi:[0,1]
	v_cmp_lt_i32_e32 vcc, s24, v30
	s_or_b64 s[8:9], vcc, s[8:9]
	v_cmp_gt_f32_e32 vcc, s17, v36
	v_pk_mul_f32 v[0:1], v[116:117], v[52:53]
	v_pk_mul_f32 v[2:3], v[118:119], v[50:51]
	v_pk_mul_f32 v[32:33], v[120:121], v[48:49]
	v_pk_mul_f32 v[28:29], v[122:123], v[28:29]
	v_cvt_pk_bf16_f32 v0, v0, v1
	v_cvt_pk_bf16_f32 v1, v2, v3
	v_cvt_pk_bf16_f32 v2, v32, v33
	v_cvt_pk_bf16_f32 v3, v28, v29
	global_store_dwordx4 v[26:27], v[0:3], off
	v_cndmask_b32_e32 v31, v36, v31, vcc
	v_rsq_f32_e32 v31, v31
	s_nop 0
	v_mul_f32_e32 v32, 0x45800000, v31
	v_cndmask_b32_e32 v32, v31, v32, vcc
	v_pk_mul_f32 v[34:35], v[32:33], v[44:45] op_sel_hi:[0,1]
	v_pk_mul_f32 v[36:37], v[32:33], v[38:39] op_sel_hi:[0,1]
	v_pk_mul_f32 v[38:39], v[32:33], v[42:43] op_sel_hi:[0,1]
	v_pk_mul_f32 v[32:33], v[32:33], v[40:41] op_sel_hi:[0,1]
	v_pk_mul_f32 v[0:1], v[124:125], v[34:35]
	v_pk_mul_f32 v[2:3], v[126:127], v[36:37]
	v_pk_mul_f32 v[26:27], v[128:129], v[38:39]
	v_pk_mul_f32 v[28:29], v[130:131], v[32:33]
	v_cvt_pk_bf16_f32 v0, v0, v1
	v_cvt_pk_bf16_f32 v1, v2, v3
	v_cvt_pk_bf16_f32 v2, v26, v27
	v_cvt_pk_bf16_f32 v3, v28, v29
	global_store_dwordx4 v[24:25], v[0:3], off
	s_andn2_b64 exec, exec, s[8:9]
	s_cbranch_execnz .LBB0_745

.LBB0_2489:
	s_waitcnt lgkmcnt(0)
	s_andn2_b64 vcc, exec, s[28:29]
	s_cbranch_vccnz .LBB0_1626
	s_add_i32 s6, s54, s16
	s_ashr_i32 s7, s6, 31
	s_lshl_b64 s[10:11], s[6:7], 12
	v_lshl_add_u64 v[2:3], v[170:171], 0, s[10:11]
	global_load_dwordx4 v[4:7], v[2:3], off
	global_load_dwordx4 v[8:11], v[2:3], off offset:64
	global_load_dwordx4 v[12:15], v[2:3], off offset:128
	global_load_dwordx4 v[16:19], v[2:3], off offset:192
	s_lshl_b32 s16, s16, 8
	v_lshl_add_u64 v[152:153], v[174:175], 0, s[16:17]
	ds_read_b32 v20, v213
	ds_read_b32 v24, v213 offset:16
	ds_read_b32 v28, v213 offset:32
	ds_read_b32 v64, v213 offset:48
	ds_read_b32 v72, v213 offset:64
	ds_read_b32 v80, v213 offset:80
	ds_read_b32 v88, v213 offset:96
	ds_read_b32 v96, v213 offset:112
	ds_read_b32 v68, v213 offset:128
	ds_read_b32 v76, v213 offset:144
	ds_read_b32 v84, v213 offset:160
	ds_read_b32 v92, v213 offset:176
	ds_read_b32 v100, v213 offset:192
	ds_read_b32 v104, v213 offset:208
	ds_read_b32 v108, v213 offset:224
	ds_read_b32 v112, v213 offset:240
	v_cmp_gt_i32_e64 s[6:7], s40, v188
	v_or_b32_e32 v2, 4, v188
	v_cmp_gt_i32_e64 s[8:9], s40, v2
	s_waitcnt lgkmcnt(0)
	v_cndmask_b32_e64 v20, 0, v20, s[6:7]
	v_ashrrev_i32_e32 v21, 31, v20
	v_lshlrev_b64 v[20:21], 7, v[20:21]
	v_lshl_add_u64 v[20:21], v[20:21], 1, v[152:153]
	global_load_dwordx4 v[20:23], v[20:21], off
	v_or_b32_e32 v0, 8, v188
	v_cmp_gt_i32_e64 s[6:7], s40, v0
	v_cndmask_b32_e64 v24, 0, v24, s[8:9]
	v_ashrrev_i32_e32 v25, 31, v24
	v_lshlrev_b64 v[24:25], 7, v[24:25]
	v_lshl_add_u64 v[24:25], v[24:25], 1, v[152:153]
	global_load_dwordx4 v[24:27], v[24:25], off
	v_or_b32_e32 v2, 12, v188
	v_cmp_gt_i32_e64 s[8:9], s40, v2
	v_cndmask_b32_e64 v28, 0, v28, s[6:7]
	v_ashrrev_i32_e32 v29, 31, v28
	v_lshlrev_b64 v[28:29], 7, v[28:29]
	v_lshl_add_u64 v[28:29], v[28:29], 1, v[152:153]
	global_load_dwordx4 v[28:31], v[28:29], off
	v_or_b32_e32 v0, 16, v188
	v_cmp_gt_i32_e64 s[6:7], s40, v0
	v_cndmask_b32_e64 v64, 0, v64, s[8:9]
	v_ashrrev_i32_e32 v65, 31, v64
	v_lshlrev_b64 v[64:65], 7, v[64:65]
	v_lshl_add_u64 v[64:65], v[64:65], 1, v[152:153]
	global_load_dwordx4 v[64:67], v[64:65], off
	v_or_b32_e32 v2, 20, v188
	v_cmp_gt_i32_e64 s[8:9], s40, v2
	v_cndmask_b32_e64 v72, 0, v72, s[6:7]
	v_ashrrev_i32_e32 v73, 31, v72
	v_lshlrev_b64 v[72:73], 7, v[72:73]
	v_lshl_add_u64 v[72:73], v[72:73], 1, v[152:153]
	global_load_dwordx4 v[72:75], v[72:73], off
	v_or_b32_e32 v0, 24, v188
	v_cmp_gt_i32_e64 s[6:7], s40, v0
	v_cndmask_b32_e64 v80, 0, v80, s[8:9]
	v_ashrrev_i32_e32 v81, 31, v80
	v_lshlrev_b64 v[80:81], 7, v[80:81]
	v_lshl_add_u64 v[80:81], v[80:81], 1, v[152:153]
	global_load_dwordx4 v[80:83], v[80:81], off
	v_or_b32_e32 v2, 28, v188
	v_cmp_gt_i32_e64 s[8:9], s40, v2
	v_cndmask_b32_e64 v88, 0, v88, s[6:7]
	v_ashrrev_i32_e32 v89, 31, v88
	v_lshlrev_b64 v[88:89], 7, v[88:89]
	v_lshl_add_u64 v[88:89], v[88:89], 1, v[152:153]
	global_load_dwordx4 v[88:91], v[88:89], off
	v_or_b32_e32 v0, 32, v188
	v_cmp_gt_i32_e64 s[6:7], s40, v0
	v_cndmask_b32_e64 v96, 0, v96, s[8:9]
	v_ashrrev_i32_e32 v97, 31, v96
	v_lshlrev_b64 v[96:97], 7, v[96:97]
	v_lshl_add_u64 v[96:97], v[96:97], 1, v[152:153]
	global_load_dwordx4 v[96:99], v[96:97], off
	v_or_b32_e32 v2, 36, v188
	v_cmp_gt_i32_e64 s[8:9], s40, v2
	v_cndmask_b32_e64 v68, 0, v68, s[6:7]
	v_ashrrev_i32_e32 v69, 31, v68
	v_lshlrev_b64 v[68:69], 7, v[68:69]
	v_lshl_add_u64 v[68:69], v[68:69], 1, v[152:153]
	global_load_dwordx4 v[68:71], v[68:69], off
	v_or_b32_e32 v0, 40, v188
	v_cmp_gt_i32_e64 s[6:7], s40, v0
	v_cndmask_b32_e64 v76, 0, v76, s[8:9]
	v_ashrrev_i32_e32 v77, 31, v76
	v_lshlrev_b64 v[76:77], 7, v[76:77]
	v_lshl_add_u64 v[76:77], v[76:77], 1, v[152:153]
	global_load_dwordx4 v[76:79], v[76:77], off
	v_or_b32_e32 v2, 44, v188
	v_cmp_gt_i32_e64 s[8:9], s40, v2
	v_cndmask_b32_e64 v84, 0, v84, s[6:7]
	v_ashrrev_i32_e32 v85, 31, v84
	v_lshlrev_b64 v[84:85], 7, v[84:85]
	v_lshl_add_u64 v[84:85], v[84:85], 1, v[152:153]
	global_load_dwordx4 v[84:87], v[84:85], off
	v_or_b32_e32 v0, 48, v188
	v_cmp_gt_i32_e64 s[6:7], s40, v0
	v_cndmask_b32_e64 v92, 0, v92, s[8:9]
	v_ashrrev_i32_e32 v93, 31, v92
	v_lshlrev_b64 v[92:93], 7, v[92:93]
	v_lshl_add_u64 v[92:93], v[92:93], 1, v[152:153]
	global_load_dwordx4 v[92:95], v[92:93], off
	v_or_b32_e32 v2, 52, v188
	v_cmp_gt_i32_e64 s[8:9], s40, v2
	v_cndmask_b32_e64 v100, 0, v100, s[6:7]
	v_ashrrev_i32_e32 v101, 31, v100
	v_lshlrev_b64 v[100:101], 7, v[100:101]
	v_lshl_add_u64 v[100:101], v[100:101], 1, v[152:153]
	global_load_dwordx4 v[100:103], v[100:101], off
	v_or_b32_e32 v0, 56, v188
	v_cmp_gt_i32_e64 s[6:7], s40, v0
	v_cndmask_b32_e64 v104, 0, v104, s[8:9]
	v_ashrrev_i32_e32 v105, 31, v104
	v_lshlrev_b64 v[104:105], 7, v[104:105]
	v_lshl_add_u64 v[104:105], v[104:105], 1, v[152:153]
	global_load_dwordx4 v[104:107], v[104:105], off
	v_or_b32_e32 v2, 60, v188
	v_cmp_gt_i32_e64 s[8:9], s40, v2
	v_cndmask_b32_e64 v108, 0, v108, s[6:7]
	v_ashrrev_i32_e32 v109, 31, v108
	v_lshlrev_b64 v[108:109], 7, v[108:109]
	v_lshl_add_u64 v[108:109], v[108:109], 1, v[152:153]
	global_load_dwordx4 v[108:111], v[108:109], off
	v_cndmask_b32_e64 v112, 0, v112, s[8:9]
	v_ashrrev_i32_e32 v113, 31, v112
	v_lshlrev_b64 v[112:113], 7, v[112:113]
	v_lshl_add_u64 v[112:113], v[112:113], 1, v[152:153]
	global_load_dwordx4 v[112:115], v[112:113], off
	s_add_i32 s6, s40, 31
	s_ashr_i32 s16, s6, 5
	s_cmp_gt_i32 s16, 0
	s_cbranch_scc0 .LBB0_1624
	v_mov_b32_e32 v2, v1
	v_mov_b32_e32 v3, v1
	v_mov_b32_e32 v0, v1
	v_mov_b32_e32 v154, 0
	v_mov_b64_e32 v[34:35], v[2:3]
	v_mov_b64_e32 v[38:39], v[2:3]
	v_mov_b64_e32 v[42:43], v[2:3]
	v_mov_b64_e32 v[46:47], v[2:3]
	v_mov_b64_e32 v[50:51], v[2:3]
	v_mov_b64_e32 v[54:55], v[2:3]
	v_mov_b64_e32 v[58:59], v[2:3]
	v_mov_b64_e32 v[62:63], v[2:3]
	s_mov_b32 s41, 0
	v_mov_b32_e32 v230, 0xff800000
	s_mov_b32 s55, 3
	s_mov_b32 s57, s42
	v_mov_b64_e32 v[32:33], v[0:1]
	v_mov_b64_e32 v[36:37], v[0:1]
	v_mov_b64_e32 v[40:41], v[0:1]
	v_mov_b64_e32 v[44:45], v[0:1]
	v_mov_b64_e32 v[48:49], v[0:1]
	v_mov_b64_e32 v[52:53], v[0:1]
	v_mov_b64_e32 v[56:57], v[0:1]
	v_mov_b64_e32 v[60:61], v[0:1]
	v_mov_b32_e32 v231, 0xff800000
	v_mov_b32_e32 v232, 0xff800000
	v_mov_b32_e32 v233, 0xff800000
	v_mov_b32_e32 v155, v154
	v_mov_b32_e32 v156, v154
	v_mov_b32_e32 v157, v154
	s_branch .LBB0_2526

.LBB0_2526:
	s_add_i32 s58, s55, -1
	s_cmp_ge_i32 s58, s16
	s_waitcnt vmcnt(0)
	ds_write_b128 v218, v[20:23]
	ds_write_b128 v218, v[24:27] offset:1088
	ds_write_b128 v218, v[28:31] offset:2176
	ds_write_b128 v218, v[64:67] offset:3264
	ds_write_b128 v218, v[72:75] offset:4352
	ds_write_b128 v218, v[80:83] offset:5440
	ds_write_b128 v218, v[88:91] offset:6528
	ds_write_b128 v218, v[96:99] offset:7616
	s_cbranch_scc1 .LBB0_2544
	v_add_u32_e32 v99, s41, v188
	v_add_u32_e32 v98, s57, v212
	v_add_u32_e32 v98, 0x20100, v98
	ds_read_b32 v20, v98
	ds_read_b32 v24, v98 offset:16
	ds_read_b32 v28, v98 offset:32
	ds_read_b32 v64, v98 offset:48
	ds_read_b32 v72, v98 offset:64
	ds_read_b32 v80, v98 offset:80
	ds_read_b32 v88, v98 offset:96
	ds_read_b32 v96, v98 offset:112
	v_add_u32_e32 v2, 64, v99
	v_cmp_gt_i32_e64 s[6:7], s40, v2
	v_add_u32_e32 v3, 0x44, v99
	v_cmp_gt_i32_e64 s[8:9], s40, v3
	s_waitcnt lgkmcnt(0)
	v_cndmask_b32_e64 v20, 0, v20, s[6:7]
	v_ashrrev_i32_e32 v21, 31, v20
	v_lshlrev_b64 v[20:21], 7, v[20:21]
	v_lshl_add_u64 v[20:21], v[20:21], 1, v[152:153]
	global_load_dwordx4 v[20:23], v[20:21], off
	v_add_u32_e32 v2, 0x48, v99
	v_cmp_gt_i32_e64 s[6:7], s40, v2
	v_cndmask_b32_e64 v24, 0, v24, s[8:9]
	v_ashrrev_i32_e32 v25, 31, v24
	v_lshlrev_b64 v[24:25], 7, v[24:25]
	v_lshl_add_u64 v[24:25], v[24:25], 1, v[152:153]
	global_load_dwordx4 v[24:27], v[24:25], off
	v_add_u32_e32 v3, 0x4c, v99
	v_cmp_gt_i32_e64 s[8:9], s40, v3
	v_cndmask_b32_e64 v28, 0, v28, s[6:7]
	v_ashrrev_i32_e32 v29, 31, v28
	v_lshlrev_b64 v[28:29], 7, v[28:29]
	v_lshl_add_u64 v[28:29], v[28:29], 1, v[152:153]
	global_load_dwordx4 v[28:31], v[28:29], off
	v_add_u32_e32 v2, 0x50, v99
	v_cmp_gt_i32_e64 s[6:7], s40, v2
	v_cndmask_b32_e64 v64, 0, v64, s[8:9]
	v_ashrrev_i32_e32 v65, 31, v64
	v_lshlrev_b64 v[64:65], 7, v[64:65]
	v_lshl_add_u64 v[64:65], v[64:65], 1, v[152:153]
	global_load_dwordx4 v[64:67], v[64:65], off
	v_add_u32_e32 v3, 0x54, v99
	v_cmp_gt_i32_e64 s[8:9], s40, v3
	v_cndmask_b32_e64 v72, 0, v72, s[6:7]
	v_ashrrev_i32_e32 v73, 31, v72
	v_lshlrev_b64 v[72:73], 7, v[72:73]
	v_lshl_add_u64 v[72:73], v[72:73], 1, v[152:153]
	global_load_dwordx4 v[72:75], v[72:73], off
	v_add_u32_e32 v2, 0x58, v99
	v_cmp_gt_i32_e64 s[6:7], s40, v2
	v_cndmask_b32_e64 v80, 0, v80, s[8:9]
	v_ashrrev_i32_e32 v81, 31, v80
	v_lshlrev_b64 v[80:81], 7, v[80:81]
	v_lshl_add_u64 v[80:81], v[80:81], 1, v[152:153]
	global_load_dwordx4 v[80:83], v[80:81], off
	v_add_u32_e32 v3, 0x5c, v99
	v_cmp_gt_i32_e64 s[8:9], s40, v3
	v_cndmask_b32_e64 v88, 0, v88, s[6:7]
	v_ashrrev_i32_e32 v89, 31, v88
	v_lshlrev_b64 v[88:89], 7, v[88:89]
	v_lshl_add_u64 v[88:89], v[88:89], 1, v[152:153]
	global_load_dwordx4 v[88:91], v[88:89], off
	v_cndmask_b32_e64 v96, 0, v96, s[8:9]
	v_ashrrev_i32_e32 v97, 31, v96
	v_lshlrev_b64 v[96:97], 7, v[96:97]
	v_lshl_add_u64 v[96:97], v[96:97], 1, v[152:153]
	global_load_dwordx4 v[96:99], v[96:97], off

.LBB0_2554:
	s_waitcnt lgkmcnt(0)
	v_mfma_f32_16x16x32_bf16 v[60:63], v[116:119], v[148:151], v[60:63]
	v_fma_f32 v2, v156, v160, v2
	v_fma_f32 v3, v157, v161, v3
	s_add_i32 s6, s55, -2
	v_pk_add_f32 v[156:157], v[158:159], v[2:3]
	v_mfma_f32_16x16x32_bf16 v[56:59], v[116:119], v[144:147], v[56:59]
	v_fma_f32 v2, v154, v184, v180
	v_fma_f32 v3, v155, v185, v181
	s_cmp_ge_i32 s6, s16
	v_pk_add_f32 v[154:155], v[182:183], v[2:3]
	v_mfma_f32_16x16x32_bf16 v[52:55], v[116:119], v[140:143], v[52:55]
	v_mfma_f32_16x16x32_bf16 v[48:51], v[116:119], v[136:139], v[48:51]
	v_mfma_f32_16x16x32_bf16 v[44:47], v[116:119], v[132:135], v[44:47]
	v_mfma_f32_16x16x32_bf16 v[40:43], v[116:119], v[128:131], v[40:43]
	v_mfma_f32_16x16x32_bf16 v[36:39], v[116:119], v[124:127], v[36:39]
	v_mfma_f32_16x16x32_bf16 v[32:35], v[116:119], v[120:123], v[32:35]
	s_cbranch_scc1 .LBB0_2524
	s_cmp_ge_i32 s55, s16
	ds_write_b128 v218, v[68:71]
	ds_write_b128 v218, v[76:79] offset:1088
	ds_write_b128 v218, v[84:87] offset:2176
	ds_write_b128 v218, v[92:95] offset:3264
	ds_write_b128 v218, v[100:103] offset:4352
	ds_write_b128 v218, v[104:107] offset:5440
	ds_write_b128 v218, v[108:111] offset:6528
	ds_write_b128 v218, v[112:115] offset:7616
	s_cbranch_scc1 .LBB0_2573
	v_add_u32_e32 v115, s41, v188
	v_add_u32_e32 v114, s57, v212
	v_add_u32_e32 v114, 0x20180, v114
	ds_read_b32 v68, v114
	ds_read_b32 v76, v114 offset:16
	ds_read_b32 v84, v114 offset:32
	ds_read_b32 v92, v114 offset:48
	ds_read_b32 v100, v114 offset:64
	ds_read_b32 v104, v114 offset:80
	ds_read_b32 v108, v114 offset:96
	ds_read_b32 v112, v114 offset:112
	v_add_u32_e32 v2, 0x60, v115
	v_cmp_gt_i32_e64 s[6:7], s40, v2
	v_add_u32_e32 v3, 0x64, v115
	v_cmp_gt_i32_e64 s[8:9], s40, v3
	s_waitcnt lgkmcnt(0)
	v_cndmask_b32_e64 v68, 0, v68, s[6:7]
	v_ashrrev_i32_e32 v69, 31, v68
	v_lshlrev_b64 v[68:69], 7, v[68:69]
	v_lshl_add_u64 v[68:69], v[68:69], 1, v[152:153]
	global_load_dwordx4 v[68:71], v[68:69], off
	v_add_u32_e32 v2, 0x68, v115
	v_cmp_gt_i32_e64 s[6:7], s40, v2
	v_cndmask_b32_e64 v76, 0, v76, s[8:9]
	v_ashrrev_i32_e32 v77, 31, v76
	v_lshlrev_b64 v[76:77], 7, v[76:77]
	v_lshl_add_u64 v[76:77], v[76:77], 1, v[152:153]
	global_load_dwordx4 v[76:79], v[76:77], off
	v_add_u32_e32 v3, 0x6c, v115
	v_cmp_gt_i32_e64 s[8:9], s40, v3
	v_cndmask_b32_e64 v84, 0, v84, s[6:7]
	v_ashrrev_i32_e32 v85, 31, v84
	v_lshlrev_b64 v[84:85], 7, v[84:85]
	v_lshl_add_u64 v[84:85], v[84:85], 1, v[152:153]
	global_load_dwordx4 v[84:87], v[84:85], off
	v_add_u32_e32 v2, 0x70, v115
	v_cmp_gt_i32_e64 s[6:7], s40, v2
	v_cndmask_b32_e64 v92, 0, v92, s[8:9]
	v_ashrrev_i32_e32 v93, 31, v92
	v_lshlrev_b64 v[92:93], 7, v[92:93]
	v_lshl_add_u64 v[92:93], v[92:93], 1, v[152:153]
	global_load_dwordx4 v[92:95], v[92:93], off
	v_add_u32_e32 v3, 0x74, v115
	v_cmp_gt_i32_e64 s[8:9], s40, v3
	v_cndmask_b32_e64 v100, 0, v100, s[6:7]
	v_ashrrev_i32_e32 v101, 31, v100
	v_lshlrev_b64 v[100:101], 7, v[100:101]
	v_lshl_add_u64 v[100:101], v[100:101], 1, v[152:153]
	global_load_dwordx4 v[100:103], v[100:101], off
	v_add_u32_e32 v2, 0x78, v115
	v_cmp_gt_i32_e64 s[6:7], s40, v2
	v_cndmask_b32_e64 v104, 0, v104, s[8:9]
	v_ashrrev_i32_e32 v105, 31, v104
	v_lshlrev_b64 v[104:105], 7, v[104:105]
	v_lshl_add_u64 v[104:105], v[104:105], 1, v[152:153]
	global_load_dwordx4 v[104:107], v[104:105], off
	v_add_u32_e32 v3, 0x7c, v115
	v_cmp_gt_i32_e64 s[8:9], s40, v3
	v_cndmask_b32_e64 v108, 0, v108, s[6:7]
	v_ashrrev_i32_e32 v109, 31, v108
	v_lshlrev_b64 v[108:109], 7, v[108:109]
	v_lshl_add_u64 v[108:109], v[108:109], 1, v[152:153]
	global_load_dwordx4 v[108:111], v[108:109], off
	v_cndmask_b32_e64 v112, 0, v112, s[8:9]
	v_ashrrev_i32_e32 v113, 31, v112
	v_lshlrev_b64 v[112:113], 7, v[112:113]
	v_lshl_add_u64 v[112:113], v[112:113], 1, v[152:153]
	global_load_dwordx4 v[112:115], v[112:113], off

.LBB0_2946:
	v_and_b32_e32 v5, 0x3fc, v2
	v_lshlrev_b32_e32 v60, 1, v5
	v_mov_b32_e32 v61, 0
	v_lshlrev_b32_e32 v62, 2, v5
	v_mov_b32_e32 v63, 0
	global_load_dwordx4 v[64:67], v62, s[8:9]
	v_lshrrev_b64 v[32:33], 8, v[0:1]
	v_lshlrev_b64 v[34:35], 6, v[32:33]
	v_lshl_add_u64 v[34:35], s[0:1], 0, v[34:35]
	global_load_dwordx4 v[40:43], v[34:35], off
	global_load_dwordx4 v[44:47], v[34:35], off offset:32
	global_load_dwordx4 v[48:51], v[34:35], off offset:16
	global_load_dwordx4 v[52:55], v[34:35], off offset:48
	v_lshlrev_b64 v[34:35], 11, v[32:33]
	v_lshl_add_u64 v[34:35], s[12:13], 0, v[34:35]
	v_lshl_add_u64 v[34:35], v[34:35], 0, v[60:61]
	global_load_dwordx2 v[56:57], v[34:35], off
	s_waitcnt vmcnt(0)
.Lfin_loop:
	v_lshrrev_b64 v[26:27], 8, v[0:1]
	v_lshlrev_b64 v[26:27], 12, v[26:27]
	v_lshl_add_u64 v[26:27], s[10:11], 0, v[26:27]
	v_lshl_add_u64 v[26:27], v[26:27], 0, v[62:63]
	v_lshl_add_u64 v[0:1], v[0:1], 0, s[14:15]
	v_cmp_lt_u64_e32 vcc, s[24:25], v[0:1]
	s_or_b64 s[16:17], vcc, s[16:17]
	s_waitcnt vmcnt(1)
	v_mov_b64_e32 v[6:7], v[40:41]
	v_mov_b64_e32 v[8:9], v[42:43]
	v_mov_b64_e32 v[10:11], v[44:45]
	v_mov_b64_e32 v[12:13], v[46:47]
	v_mov_b64_e32 v[14:15], v[48:49]
	v_mov_b64_e32 v[16:17], v[50:51]
	v_mov_b64_e32 v[18:19], v[52:53]
	v_mov_b64_e32 v[20:21], v[54:55]
	v_mov_b64_e32 v[30:31], v[56:57]
	v_lshrrev_b64 v[32:33], 8, v[0:1]
	v_min_u32_e32 v32, 0x7fff, v32
	v_lshlrev_b64 v[34:35], 6, v[32:33]
	v_lshl_add_u64 v[34:35], s[0:1], 0, v[34:35]
	global_load_dwordx4 v[40:43], v[34:35], off
	global_load_dwordx4 v[44:47], v[34:35], off offset:32
	global_load_dwordx4 v[48:51], v[34:35], off offset:16
	global_load_dwordx4 v[52:55], v[34:35], off offset:48
	v_lshlrev_b64 v[34:35], 11, v[32:33]
	v_lshl_add_u64 v[34:35], s[12:13], 0, v[34:35]
	v_lshl_add_u64 v[34:35], v[34:35], 0, v[60:61]
	global_load_dwordx2 v[56:57], v[34:35], off
	v_mov_b32_e32 v28, v6
	v_mov_b32_e32 v29, v10
	v_mov_b32_e32 v10, v7
	v_mov_b32_e32 v6, v8
	v_mov_b32_e32 v7, v12
	v_mov_b32_e32 v12, v9
	v_mov_b32_e32 v8, v14
	v_mov_b32_e32 v9, v18
	v_mov_b32_e32 v18, v15
	v_mov_b32_e32 v14, v16
	v_mov_b32_e32 v15, v20
	v_mov_b32_e32 v20, v17
	v_pk_add_f32 v[10:11], v[28:29], v[10:11]
	v_pk_add_f32 v[6:7], v[6:7], v[12:13]
	v_pk_add_f32 v[8:9], v[8:9], v[18:19]
	v_pk_add_f32 v[12:13], v[14:15], v[20:21]
	v_pk_add_f32 v[6:7], v[10:11], v[6:7]
	v_pk_add_f32 v[8:9], v[8:9], v[12:13]
	v_lshlrev_b32_e32 v14, 16, v30
	v_pk_add_f32 v[6:7], v[6:7], v[8:9]
	v_and_b32_e32 v15, 0xffff0000, v30
	v_add_f32_e32 v5, v6, v7
	v_fmamk_f32 v5, v5, 0x3a800000, v4
	v_mul_f32_e32 v6, 0x4b800000, v5
	v_cmp_gt_f32_e32 vcc, s26, v5
	v_lshlrev_b32_e32 v16, 16, v31
	v_and_b32_e32 v17, 0xffff0000, v31
	v_cndmask_b32_e32 v5, v5, v6, vcc
	v_rsq_f32_e32 v5, v5
	s_nop 0
	v_mul_f32_e32 v6, 0x45800000, v5
	v_cndmask_b32_e32 v6, v5, v6, vcc
	v_pk_mul_f32 v[10:11], v[6:7], v[14:15] op_sel_hi:[0,1]
	v_pk_mul_f32 v[6:7], v[6:7], v[16:17] op_sel_hi:[0,1]
	v_pk_mul_f32 v[8:9], v[66:67], v[6:7]
	v_pk_mul_f32 v[6:7], v[64:65], v[10:11]
	global_store_dwordx4 v[26:27], v[6:9], off
	s_andn2_b64 exec, exec, s[16:17]
	s_cbranch_execnz .Lfin_loop
